# in-proj epilogues: row scale via v_rsq_f32 (as the reference's rsqrt) instead of the f32 sqrt + IEEE divide expansion (33 VALU per row block)
# speedup vs baseline: 1.0177x; 1.0058x over previous
.LBB0_221:
	v_lshl_add_u32 v18, s89, 8, v207
	v_ashrrev_i32_e32 v19, 31, v18
	v_lshrrev_b32_e32 v2, 6, v218
	v_and_b32_e32 v3, 15, v218
	v_lshlrev_b32_e32 v3, 2, v3
	v_lshl_add_u32 v2, v2, 10, v3
	v_add_u32_e32 v2, 0x20000, v2
	ds_read_b32 v0, v2
	ds_read_b32 v31, v2 offset:64
	ds_read_b32 v30, v2 offset:128
	ds_read_b32 v29, v2 offset:192
	ds_read_b32 v28, v2 offset:512
	ds_read_b32 v27, v2 offset:576
	ds_read_b32 v26, v2 offset:640
	ds_read_b32 v19, v2 offset:704
	v_lshl_or_b32 v16, s88, 8, v209
	v_ashrrev_i32_e32 v17, 31, v16
	s_cmp_lt_i32 s31, 3
	s_waitcnt lgkmcnt(0)
	v_fmamk_f32 v0, v0, 0x3a800000, v219
	v_rsq_f32_e32 v1, v0
	s_nop 0
	v_mul_f32_e32 v22, s81, v1
	v_mov_b64_e32 v[0:1], s[42:43]
	v_mad_i64_i32 v[20:21], s[8:9], v18, s70, v[0:1]
	v_pk_mul_f32 v[2:3], v[160:161], v[22:23] op_sel_hi:[1,0]
	v_pk_mul_f32 v[0:1], v[158:159], v[22:23] op_sel_hi:[1,0]
	v_pk_mul_f32 v[6:7], v[156:157], v[22:23] op_sel_hi:[1,0]
	v_pk_mul_f32 v[4:5], v[154:155], v[22:23] op_sel_hi:[1,0]
	s_cbranch_scc1 .LBB0_224
	s_cmp_gt_i32 s31, 3
	s_cbranch_scc0 .LBB0_225
	v_pk_mul_f32 v[10:11], v[2:3], s[78:79] op_sel_hi:[1,0]
	v_pk_mul_f32 v[8:9], v[0:1], s[78:79] op_sel_hi:[1,0]
	v_pk_mul_f32 v[14:15], v[6:7], s[78:79] op_sel_hi:[1,0]
	v_pk_mul_f32 v[12:13], v[4:5], s[78:79] op_sel_hi:[1,0]
	s_mov_b64 s[10:11], -1
	s_cbranch_execz .LBB0_226
	s_branch .LBB0_227

.LBB0_253:
	s_nop 1
	v_fmamk_f32 v0, v31, 0x3a800000, v219
	s_cmp_lt_i32 s31, 3
	v_rsq_f32_e32 v1, v0
	v_or_b32_e32 v3, 16, v18
	s_nop 0
	v_mul_f32_e32 v22, s81, v1
	v_mov_b64_e32 v[0:1], s[42:43]
	v_mad_i64_i32 v[20:21], s[8:9], v3, s70, v[0:1]
	v_pk_mul_f32 v[2:3], v[144:145], v[22:23] op_sel_hi:[1,0]
	v_pk_mul_f32 v[0:1], v[142:143], v[22:23] op_sel_hi:[1,0]
	v_pk_mul_f32 v[6:7], v[140:141], v[22:23] op_sel_hi:[1,0]
	v_pk_mul_f32 v[4:5], v[138:139], v[22:23] op_sel_hi:[1,0]
	s_cbranch_scc1 .LBB0_256
	s_cmp_gt_i32 s31, 3
	s_cbranch_scc0 .LBB0_257
	v_pk_mul_f32 v[10:11], v[2:3], s[78:79] op_sel_hi:[1,0]
	v_pk_mul_f32 v[8:9], v[0:1], s[78:79] op_sel_hi:[1,0]
	v_pk_mul_f32 v[14:15], v[6:7], s[78:79] op_sel_hi:[1,0]
	v_pk_mul_f32 v[12:13], v[4:5], s[78:79] op_sel_hi:[1,0]
	s_mov_b64 s[10:11], -1
	s_cbranch_execz .LBB0_258
	s_branch .LBB0_259

.LBB0_285:
	s_nop 1
	v_fmamk_f32 v0, v30, 0x3a800000, v219
	s_cmp_lt_i32 s31, 3
	v_rsq_f32_e32 v1, v0
	v_or_b32_e32 v3, 32, v18
	s_nop 0
	v_mul_f32_e32 v22, s81, v1
	v_mov_b64_e32 v[0:1], s[42:43]
	v_mad_i64_i32 v[20:21], s[8:9], v3, s70, v[0:1]
	v_pk_mul_f32 v[2:3], v[128:129], v[22:23] op_sel_hi:[1,0]
	v_pk_mul_f32 v[0:1], v[126:127], v[22:23] op_sel_hi:[1,0]
	v_pk_mul_f32 v[6:7], v[124:125], v[22:23] op_sel_hi:[1,0]
	v_pk_mul_f32 v[4:5], v[122:123], v[22:23] op_sel_hi:[1,0]
	s_cbranch_scc1 .LBB0_288
	s_cmp_gt_i32 s31, 3
	s_cbranch_scc0 .LBB0_289
	v_pk_mul_f32 v[10:11], v[2:3], s[78:79] op_sel_hi:[1,0]
	v_pk_mul_f32 v[8:9], v[0:1], s[78:79] op_sel_hi:[1,0]
	v_pk_mul_f32 v[14:15], v[6:7], s[78:79] op_sel_hi:[1,0]
	v_pk_mul_f32 v[12:13], v[4:5], s[78:79] op_sel_hi:[1,0]
	s_mov_b64 s[10:11], -1
	s_cbranch_execz .LBB0_290
	s_branch .LBB0_291

.LBB0_317:
	s_nop 1
	v_fmamk_f32 v0, v29, 0x3a800000, v219
	s_cmp_lt_i32 s31, 3
	v_rsq_f32_e32 v1, v0
	v_or_b32_e32 v3, 48, v18
	s_nop 0
	v_mul_f32_e32 v22, s81, v1
	v_mov_b64_e32 v[0:1], s[42:43]
	v_mad_i64_i32 v[20:21], s[8:9], v3, s70, v[0:1]
	v_pk_mul_f32 v[2:3], v[112:113], v[22:23] op_sel_hi:[1,0]
	v_pk_mul_f32 v[0:1], v[110:111], v[22:23] op_sel_hi:[1,0]
	v_pk_mul_f32 v[6:7], v[108:109], v[22:23] op_sel_hi:[1,0]
	v_pk_mul_f32 v[4:5], v[106:107], v[22:23] op_sel_hi:[1,0]
	s_cbranch_scc1 .LBB0_320
	s_cmp_gt_i32 s31, 3
	s_cbranch_scc0 .LBB0_321
	v_pk_mul_f32 v[10:11], v[2:3], s[78:79] op_sel_hi:[1,0]
	v_pk_mul_f32 v[8:9], v[0:1], s[78:79] op_sel_hi:[1,0]
	v_pk_mul_f32 v[14:15], v[6:7], s[78:79] op_sel_hi:[1,0]
	v_pk_mul_f32 v[12:13], v[4:5], s[78:79] op_sel_hi:[1,0]
	s_mov_b64 s[10:11], -1
	s_cbranch_execz .LBB0_322
	s_branch .LBB0_323

.LBB0_349:
	s_nop 1
	v_fmamk_f32 v0, v28, 0x3a800000, v219
	s_cmp_lt_i32 s31, 3
	v_rsq_f32_e32 v1, v0
	v_add_u32_e32 v3, 0x80, v18
	s_nop 0
	v_mul_f32_e32 v22, s81, v1
	v_mov_b64_e32 v[0:1], s[42:43]
	v_mad_i64_i32 v[20:21], s[8:9], v3, s70, v[0:1]
	v_pk_mul_f32 v[2:3], v[96:97], v[22:23] op_sel_hi:[1,0]
	v_pk_mul_f32 v[0:1], v[94:95], v[22:23] op_sel_hi:[1,0]
	v_pk_mul_f32 v[6:7], v[92:93], v[22:23] op_sel_hi:[1,0]
	v_pk_mul_f32 v[4:5], v[90:91], v[22:23] op_sel_hi:[1,0]
	s_cbranch_scc1 .LBB0_352
	s_cmp_gt_i32 s31, 3
	s_cbranch_scc0 .LBB0_353
	v_pk_mul_f32 v[10:11], v[2:3], s[78:79] op_sel_hi:[1,0]
	v_pk_mul_f32 v[8:9], v[0:1], s[78:79] op_sel_hi:[1,0]
	v_pk_mul_f32 v[14:15], v[6:7], s[78:79] op_sel_hi:[1,0]
	v_pk_mul_f32 v[12:13], v[4:5], s[78:79] op_sel_hi:[1,0]
	s_mov_b64 s[10:11], -1
	s_cbranch_execz .LBB0_354
	s_branch .LBB0_355

.LBB0_381:
	s_nop 1
	v_fmamk_f32 v0, v27, 0x3a800000, v219
	s_cmp_lt_i32 s31, 3
	v_rsq_f32_e32 v1, v0
	v_add_u32_e32 v3, 0x90, v18
	s_nop 0
	v_mul_f32_e32 v22, s81, v1
	v_mov_b64_e32 v[0:1], s[42:43]
	v_mad_i64_i32 v[20:21], s[8:9], v3, s70, v[0:1]
	v_pk_mul_f32 v[2:3], v[80:81], v[22:23] op_sel_hi:[1,0]
	v_pk_mul_f32 v[0:1], v[78:79], v[22:23] op_sel_hi:[1,0]
	v_pk_mul_f32 v[6:7], v[76:77], v[22:23] op_sel_hi:[1,0]
	v_pk_mul_f32 v[4:5], v[74:75], v[22:23] op_sel_hi:[1,0]
	s_cbranch_scc1 .LBB0_384
	s_cmp_gt_i32 s31, 3
	s_cbranch_scc0 .LBB0_385
	v_pk_mul_f32 v[10:11], v[2:3], s[78:79] op_sel_hi:[1,0]
	v_pk_mul_f32 v[8:9], v[0:1], s[78:79] op_sel_hi:[1,0]
	v_pk_mul_f32 v[14:15], v[6:7], s[78:79] op_sel_hi:[1,0]
	v_pk_mul_f32 v[12:13], v[4:5], s[78:79] op_sel_hi:[1,0]
	s_mov_b64 s[10:11], -1
	s_cbranch_execz .LBB0_386
	s_branch .LBB0_387

.LBB0_413:
	s_nop 1
	v_fmamk_f32 v0, v26, 0x3a800000, v219
	s_cmp_lt_i32 s31, 3
	v_rsq_f32_e32 v1, v0
	v_add_u32_e32 v3, 0xa0, v18
	s_nop 0
	v_mul_f32_e32 v22, s81, v1
	v_mov_b64_e32 v[0:1], s[42:43]
	v_mad_i64_i32 v[20:21], s[8:9], v3, s70, v[0:1]
	v_pk_mul_f32 v[2:3], v[64:65], v[22:23] op_sel_hi:[1,0]
	v_pk_mul_f32 v[0:1], v[62:63], v[22:23] op_sel_hi:[1,0]
	v_pk_mul_f32 v[6:7], v[60:61], v[22:23] op_sel_hi:[1,0]
	v_pk_mul_f32 v[4:5], v[58:59], v[22:23] op_sel_hi:[1,0]
	s_cbranch_scc1 .LBB0_416
	s_cmp_gt_i32 s31, 3
	s_cbranch_scc0 .LBB0_417
	v_pk_mul_f32 v[10:11], v[2:3], s[78:79] op_sel_hi:[1,0]
	v_pk_mul_f32 v[8:9], v[0:1], s[78:79] op_sel_hi:[1,0]
	v_pk_mul_f32 v[14:15], v[6:7], s[78:79] op_sel_hi:[1,0]
	v_pk_mul_f32 v[12:13], v[4:5], s[78:79] op_sel_hi:[1,0]
	s_mov_b64 s[10:11], -1
	s_cbranch_execz .LBB0_418
	s_branch .LBB0_419

.LBB0_445:
	s_nop 1
	v_fmamk_f32 v0, v19, 0x3a800000, v219
	s_cmp_lt_i32 s31, 3
	v_rsq_f32_e32 v1, v0
	v_add_u32_e32 v3, 0xb0, v18
	s_nop 0
	v_mul_f32_e32 v20, s81, v1
	v_mov_b64_e32 v[0:1], s[42:43]
	v_mad_i64_i32 v[18:19], s[8:9], v3, s70, v[0:1]
	v_pk_mul_f32 v[2:3], v[48:49], v[20:21] op_sel_hi:[1,0]
	v_pk_mul_f32 v[0:1], v[46:47], v[20:21] op_sel_hi:[1,0]
	v_pk_mul_f32 v[6:7], v[44:45], v[20:21] op_sel_hi:[1,0]
	v_pk_mul_f32 v[4:5], v[42:43], v[20:21] op_sel_hi:[1,0]
	s_cbranch_scc1 .LBB0_448
	s_cmp_gt_i32 s31, 3
	s_cbranch_scc0 .LBB0_449
	v_pk_mul_f32 v[10:11], v[2:3], s[78:79] op_sel_hi:[1,0]
	v_pk_mul_f32 v[8:9], v[0:1], s[78:79] op_sel_hi:[1,0]
	v_pk_mul_f32 v[14:15], v[6:7], s[78:79] op_sel_hi:[1,0]
	v_pk_mul_f32 v[12:13], v[4:5], s[78:79] op_sel_hi:[1,0]
	s_mov_b64 s[10:11], -1
	s_cbranch_execz .LBB0_450
	s_branch .LBB0_451

.LBB0_493:
	v_lshl_or_b32 v32, s44, 6, v213
	v_readlane_b32 s8, v254, 34
	s_cmp_lt_i32 s2, 3
	s_nop 0
	v_add_u32_e32 v76, s8, v32
	v_ashrrev_i32_e32 v77, 31, v76
	v_lshl_add_u64 v[68:69], v[76:77], 2, s[12:13]
	global_load_dword v66, v[68:69], off
	global_load_dword v84, v[68:69], off offset:64
	global_load_dword v77, v[68:69], off offset:128
	global_load_dword v32, v[68:69], off offset:192
	v_readlane_b32 s8, v254, 35
	s_waitcnt vmcnt(0)
	v_fmamk_f32 v66, v66, 0x3a800000, v219
	v_or_b32_e32 v67, s8, v212
	v_or_b32_e32 v74, s45, v67
	v_ashrrev_i32_e32 v75, 31, v74
	v_rsq_f32_e32 v67, v66
	s_nop 0
	v_mul_f32_e32 v80, s81, v67
	v_mov_b64_e32 v[66:67], s[42:43]
	v_mad_i64_i32 v[78:79], s[8:9], v76, s70, v[66:67]
	v_pk_mul_f32 v[64:65], v[64:65], v[80:81] op_sel_hi:[1,0]
	v_pk_mul_f32 v[62:63], v[62:63], v[80:81] op_sel_hi:[1,0]
	v_pk_mul_f32 v[60:61], v[60:61], v[80:81] op_sel_hi:[1,0]
	v_pk_mul_f32 v[58:59], v[58:59], v[80:81] op_sel_hi:[1,0]
	s_cbranch_scc1 .LBB0_498
	s_cmp_gt_i32 s2, 3
	s_cbranch_scc0 .LBB0_499
	v_mov_b64_e32 v[72:73], v[60:61]
	v_mov_b64_e32 v[68:69], v[64:65]
	s_cmp_eq_u32 s2, 4
	v_mov_b64_e32 v[70:71], v[58:59]
	v_mov_b64_e32 v[66:67], v[62:63]
	s_cbranch_scc0 .LBB0_497
	v_pk_mul_f32 v[68:69], v[64:65], s[78:79] op_sel_hi:[1,0]
	v_pk_mul_f32 v[66:67], v[62:63], s[78:79] op_sel_hi:[1,0]
	v_pk_mul_f32 v[72:73], v[60:61], s[78:79] op_sel_hi:[1,0]
	v_pk_mul_f32 v[70:71], v[58:59], s[78:79] op_sel_hi:[1,0]

.LBB0_529:
	s_nop 1
	v_fmamk_f32 v50, v84, 0x3a800000, v219
	s_cmp_lt_i32 s2, 3
	v_rsq_f32_e32 v51, v50
	v_or_b32_e32 v53, 16, v76
	s_nop 0
	v_mul_f32_e32 v60, s81, v51
	v_mov_b64_e32 v[50:51], s[42:43]
	v_mad_i64_i32 v[58:59], s[8:9], v53, s70, v[50:51]
	v_pk_mul_f32 v[48:49], v[48:49], v[60:61] op_sel_hi:[1,0]
	v_pk_mul_f32 v[46:47], v[46:47], v[60:61] op_sel_hi:[1,0]
	v_pk_mul_f32 v[44:45], v[44:45], v[60:61] op_sel_hi:[1,0]
	v_pk_mul_f32 v[42:43], v[42:43], v[60:61] op_sel_hi:[1,0]
	s_cbranch_scc1 .LBB0_534
	s_cmp_gt_i32 s2, 3
	s_cbranch_scc0 .LBB0_535
	v_mov_b64_e32 v[56:57], v[44:45]
	v_mov_b64_e32 v[52:53], v[48:49]
	s_cmp_eq_u32 s2, 4
	v_mov_b64_e32 v[54:55], v[42:43]
	v_mov_b64_e32 v[50:51], v[46:47]
	s_cbranch_scc0 .LBB0_533
	v_pk_mul_f32 v[52:53], v[48:49], s[78:79] op_sel_hi:[1,0]
	v_pk_mul_f32 v[50:51], v[46:47], s[78:79] op_sel_hi:[1,0]
	v_pk_mul_f32 v[56:57], v[44:45], s[78:79] op_sel_hi:[1,0]
	v_pk_mul_f32 v[54:55], v[42:43], s[78:79] op_sel_hi:[1,0]

.LBB0_565:
	s_nop 1
	v_fmamk_f32 v34, v77, 0x3a800000, v219
	s_cmp_lt_i32 s2, 3
	v_rsq_f32_e32 v35, v34
	v_or_b32_e32 v37, 32, v76
	s_nop 0
	v_mul_f32_e32 v44, s81, v35
	v_mov_b64_e32 v[34:35], s[42:43]
	v_mad_i64_i32 v[42:43], s[8:9], v37, s70, v[34:35]
	v_pk_mul_f32 v[30:31], v[30:31], v[44:45] op_sel_hi:[1,0]
	v_pk_mul_f32 v[28:29], v[28:29], v[44:45] op_sel_hi:[1,0]
	v_pk_mul_f32 v[26:27], v[26:27], v[44:45] op_sel_hi:[1,0]
	v_pk_mul_f32 v[24:25], v[24:25], v[44:45] op_sel_hi:[1,0]
	s_cbranch_scc1 .LBB0_570
	s_cmp_gt_i32 s2, 3
	s_cbranch_scc0 .LBB0_571
	v_mov_b64_e32 v[40:41], v[26:27]
	v_mov_b64_e32 v[36:37], v[30:31]
	s_cmp_eq_u32 s2, 4
	v_mov_b64_e32 v[38:39], v[24:25]
	v_mov_b64_e32 v[34:35], v[28:29]
	s_cbranch_scc0 .LBB0_569
	v_pk_mul_f32 v[36:37], v[30:31], s[78:79] op_sel_hi:[1,0]
	v_pk_mul_f32 v[34:35], v[28:29], s[78:79] op_sel_hi:[1,0]
	v_pk_mul_f32 v[40:41], v[26:27], s[78:79] op_sel_hi:[1,0]
	v_pk_mul_f32 v[38:39], v[24:25], s[78:79] op_sel_hi:[1,0]

.LBB0_601:
	s_nop 1
	v_fmamk_f32 v16, v32, 0x3a800000, v219
	s_cmp_lt_i32 s2, 3
	v_rsq_f32_e32 v17, v16
	v_or_b32_e32 v19, 48, v76
	s_nop 0
	v_mul_f32_e32 v26, s81, v17
	v_mov_b64_e32 v[16:17], s[42:43]
	v_mad_i64_i32 v[24:25], s[8:9], v19, s70, v[16:17]
	v_pk_mul_f32 v[14:15], v[14:15], v[26:27] op_sel_hi:[1,0]
	v_pk_mul_f32 v[12:13], v[12:13], v[26:27] op_sel_hi:[1,0]
	v_pk_mul_f32 v[10:11], v[10:11], v[26:27] op_sel_hi:[1,0]
	v_pk_mul_f32 v[8:9], v[8:9], v[26:27] op_sel_hi:[1,0]
	s_cbranch_scc1 .LBB0_606
	s_cmp_gt_i32 s2, 3
	s_cbranch_scc0 .LBB0_607
	v_mov_b64_e32 v[22:23], v[10:11]
	v_mov_b64_e32 v[18:19], v[14:15]
	s_cmp_eq_u32 s2, 4
	v_mov_b64_e32 v[20:21], v[8:9]
	v_mov_b64_e32 v[16:17], v[12:13]
	s_cbranch_scc0 .LBB0_605
	v_pk_mul_f32 v[18:19], v[14:15], s[78:79] op_sel_hi:[1,0]
	v_pk_mul_f32 v[16:17], v[12:13], s[78:79] op_sel_hi:[1,0]
	v_pk_mul_f32 v[22:23], v[10:11], s[78:79] op_sel_hi:[1,0]
	v_pk_mul_f32 v[20:21], v[8:9], s[78:79] op_sel_hi:[1,0]

.LBB0_661:
	v_lshl_add_u32 v150, s88, 8, v158
	v_ashrrev_i32_e32 v151, 31, v150
	v_lshrrev_b32_e32 v132, 6, v218
	v_and_b32_e32 v133, 15, v218
	v_lshlrev_b32_e32 v133, 2, v133
	v_lshl_add_u32 v132, v132, 10, v133
	v_add_u32_e32 v132, 0x20000, v132
	ds_read_b32 v130, v132
	ds_read_b32 v167, v132 offset:64
	ds_read_b32 v166, v132 offset:128
	ds_read_b32 v165, v132 offset:192
	ds_read_b32 v164, v132 offset:512
	ds_read_b32 v163, v132 offset:576
	ds_read_b32 v162, v132 offset:640
	ds_read_b32 v151, v132 offset:704
	v_lshl_or_b32 v148, s87, 8, v160
	v_ashrrev_i32_e32 v149, 31, v148
	s_cmp_lt_i32 s19, 3
	s_mov_b32 s73, 0x3b000000
	s_waitcnt lgkmcnt(0)
	v_fmamk_f32 v130, v130, 0x3a800000, v219
	v_rsq_f32_e32 v131, v130
	s_nop 0
	v_mov_b32_e32 v154, v131
	v_mov_b64_e32 v[130:131], s[42:43]
	v_mad_i64_i32 v[152:153], s[8:9], v150, s70, v[130:131]
	v_pk_mul_f32 v[128:129], v[128:129], v[154:155] op_sel_hi:[1,0]
	v_pk_mul_f32 v[126:127], v[126:127], v[154:155] op_sel_hi:[1,0]
	v_pk_mul_f32 v[124:125], v[124:125], v[154:155] op_sel_hi:[1,0]
	v_pk_mul_f32 v[122:123], v[122:123], v[154:155] op_sel_hi:[1,0]
	s_cbranch_scc1 .LBB0_664
	s_cmp_gt_i32 s19, 3
	s_cbranch_scc0 .LBB0_665
	v_pk_mul_f32 v[132:133], v[128:129], s[78:79] op_sel_hi:[1,0]
	v_pk_mul_f32 v[130:131], v[126:127], s[78:79] op_sel_hi:[1,0]
	v_pk_mul_f32 v[136:137], v[124:125], s[78:79] op_sel_hi:[1,0]
	v_pk_mul_f32 v[134:135], v[122:123], s[78:79] op_sel_hi:[1,0]
	s_mov_b64 s[10:11], -1
	s_cbranch_execz .LBB0_666
	s_branch .LBB0_667

.LBB0_693:
	s_nop 1
	v_fmamk_f32 v114, v167, 0x3a800000, v219
	s_cmp_lt_i32 s19, 3
	v_rsq_f32_e32 v115, v114
	v_or_b32_e32 v117, 16, v150
	s_nop 0
	v_mov_b32_e32 v124, v115
	v_mov_b64_e32 v[114:115], s[42:43]
	v_mad_i64_i32 v[122:123], s[8:9], v117, s70, v[114:115]
	v_pk_mul_f32 v[112:113], v[112:113], v[124:125] op_sel_hi:[1,0]
	v_pk_mul_f32 v[110:111], v[110:111], v[124:125] op_sel_hi:[1,0]
	v_pk_mul_f32 v[108:109], v[108:109], v[124:125] op_sel_hi:[1,0]
	v_pk_mul_f32 v[106:107], v[106:107], v[124:125] op_sel_hi:[1,0]
	s_cbranch_scc1 .LBB0_696
	s_cmp_gt_i32 s19, 3
	s_cbranch_scc0 .LBB0_697
	v_pk_mul_f32 v[116:117], v[112:113], s[78:79] op_sel_hi:[1,0]
	v_pk_mul_f32 v[114:115], v[110:111], s[78:79] op_sel_hi:[1,0]
	v_pk_mul_f32 v[120:121], v[108:109], s[78:79] op_sel_hi:[1,0]
	v_pk_mul_f32 v[118:119], v[106:107], s[78:79] op_sel_hi:[1,0]
	s_mov_b64 s[10:11], -1
	s_cbranch_execz .LBB0_698
	s_branch .LBB0_699

.LBB0_725:
	s_nop 1
	v_fmamk_f32 v98, v166, 0x3a800000, v219
	s_cmp_lt_i32 s19, 3
	v_rsq_f32_e32 v99, v98
	v_or_b32_e32 v101, 32, v150
	s_nop 0
	v_mov_b32_e32 v108, v99
	v_mov_b64_e32 v[98:99], s[42:43]
	v_mad_i64_i32 v[106:107], s[8:9], v101, s70, v[98:99]
	v_pk_mul_f32 v[96:97], v[96:97], v[108:109] op_sel_hi:[1,0]
	v_pk_mul_f32 v[94:95], v[94:95], v[108:109] op_sel_hi:[1,0]
	v_pk_mul_f32 v[92:93], v[92:93], v[108:109] op_sel_hi:[1,0]
	v_pk_mul_f32 v[90:91], v[90:91], v[108:109] op_sel_hi:[1,0]
	s_cbranch_scc1 .LBB0_728
	s_cmp_gt_i32 s19, 3
	s_cbranch_scc0 .LBB0_729
	v_pk_mul_f32 v[100:101], v[96:97], s[78:79] op_sel_hi:[1,0]
	v_pk_mul_f32 v[98:99], v[94:95], s[78:79] op_sel_hi:[1,0]
	v_pk_mul_f32 v[104:105], v[92:93], s[78:79] op_sel_hi:[1,0]
	v_pk_mul_f32 v[102:103], v[90:91], s[78:79] op_sel_hi:[1,0]
	s_mov_b64 s[10:11], -1
	s_cbranch_execz .LBB0_730
	s_branch .LBB0_731

.LBB0_757:
	s_nop 1
	v_fmamk_f32 v82, v165, 0x3a800000, v219
	s_cmp_lt_i32 s19, 3
	v_rsq_f32_e32 v83, v82
	v_or_b32_e32 v85, 48, v150
	s_nop 0
	v_mov_b32_e32 v92, v83
	v_mov_b64_e32 v[82:83], s[42:43]
	v_mad_i64_i32 v[90:91], s[8:9], v85, s70, v[82:83]
	v_pk_mul_f32 v[80:81], v[80:81], v[92:93] op_sel_hi:[1,0]
	v_pk_mul_f32 v[78:79], v[78:79], v[92:93] op_sel_hi:[1,0]
	v_pk_mul_f32 v[76:77], v[76:77], v[92:93] op_sel_hi:[1,0]
	v_pk_mul_f32 v[74:75], v[74:75], v[92:93] op_sel_hi:[1,0]
	s_cbranch_scc1 .LBB0_760
	s_cmp_gt_i32 s19, 3
	s_cbranch_scc0 .LBB0_761
	v_pk_mul_f32 v[84:85], v[80:81], s[78:79] op_sel_hi:[1,0]
	v_pk_mul_f32 v[82:83], v[78:79], s[78:79] op_sel_hi:[1,0]
	v_pk_mul_f32 v[88:89], v[76:77], s[78:79] op_sel_hi:[1,0]
	v_pk_mul_f32 v[86:87], v[74:75], s[78:79] op_sel_hi:[1,0]
	s_mov_b64 s[10:11], -1
	s_cbranch_execz .LBB0_762
	s_branch .LBB0_763

.LBB0_789:
	s_nop 1
	v_fmamk_f32 v66, v164, 0x3a800000, v219
	s_cmp_lt_i32 s19, 3
	v_rsq_f32_e32 v67, v66
	v_add_u32_e32 v69, 0x80, v150
	s_nop 0
	v_mov_b32_e32 v76, v67
	v_mov_b64_e32 v[66:67], s[42:43]
	v_mad_i64_i32 v[74:75], s[8:9], v69, s70, v[66:67]
	v_pk_mul_f32 v[64:65], v[64:65], v[76:77] op_sel_hi:[1,0]
	v_pk_mul_f32 v[62:63], v[62:63], v[76:77] op_sel_hi:[1,0]
	v_pk_mul_f32 v[60:61], v[60:61], v[76:77] op_sel_hi:[1,0]
	v_pk_mul_f32 v[58:59], v[58:59], v[76:77] op_sel_hi:[1,0]
	s_cbranch_scc1 .LBB0_792
	s_cmp_gt_i32 s19, 3
	s_cbranch_scc0 .LBB0_793
	v_pk_mul_f32 v[68:69], v[64:65], s[78:79] op_sel_hi:[1,0]
	v_pk_mul_f32 v[66:67], v[62:63], s[78:79] op_sel_hi:[1,0]
	v_pk_mul_f32 v[72:73], v[60:61], s[78:79] op_sel_hi:[1,0]
	v_pk_mul_f32 v[70:71], v[58:59], s[78:79] op_sel_hi:[1,0]
	s_mov_b64 s[10:11], -1
	s_cbranch_execz .LBB0_794
	s_branch .LBB0_795

.LBB0_821:
	s_nop 1
	v_fmamk_f32 v50, v163, 0x3a800000, v219
	s_cmp_lt_i32 s19, 3
	v_rsq_f32_e32 v51, v50
	v_add_u32_e32 v53, 0x90, v150
	s_nop 0
	v_mov_b32_e32 v60, v51
	v_mov_b64_e32 v[50:51], s[42:43]
	v_mad_i64_i32 v[58:59], s[8:9], v53, s70, v[50:51]
	v_pk_mul_f32 v[48:49], v[48:49], v[60:61] op_sel_hi:[1,0]
	v_pk_mul_f32 v[46:47], v[46:47], v[60:61] op_sel_hi:[1,0]
	v_pk_mul_f32 v[44:45], v[44:45], v[60:61] op_sel_hi:[1,0]
	v_pk_mul_f32 v[42:43], v[42:43], v[60:61] op_sel_hi:[1,0]
	s_cbranch_scc1 .LBB0_824
	s_cmp_gt_i32 s19, 3
	s_cbranch_scc0 .LBB0_825
	v_pk_mul_f32 v[52:53], v[48:49], s[78:79] op_sel_hi:[1,0]
	v_pk_mul_f32 v[50:51], v[46:47], s[78:79] op_sel_hi:[1,0]
	v_pk_mul_f32 v[56:57], v[44:45], s[78:79] op_sel_hi:[1,0]
	v_pk_mul_f32 v[54:55], v[42:43], s[78:79] op_sel_hi:[1,0]
	s_mov_b64 s[10:11], -1
	s_cbranch_execz .LBB0_826
	s_branch .LBB0_827

.LBB0_853:
	s_nop 1
	v_fmamk_f32 v34, v162, 0x3a800000, v219
	s_cmp_lt_i32 s19, 3
	v_rsq_f32_e32 v35, v34
	v_add_u32_e32 v37, 0xa0, v150
	s_nop 0
	v_mov_b32_e32 v44, v35
	v_mov_b64_e32 v[34:35], s[42:43]
	v_mad_i64_i32 v[42:43], s[8:9], v37, s70, v[34:35]
	v_pk_mul_f32 v[30:31], v[30:31], v[44:45] op_sel_hi:[1,0]
	v_pk_mul_f32 v[28:29], v[28:29], v[44:45] op_sel_hi:[1,0]
	v_pk_mul_f32 v[26:27], v[26:27], v[44:45] op_sel_hi:[1,0]
	v_pk_mul_f32 v[24:25], v[24:25], v[44:45] op_sel_hi:[1,0]
	s_cbranch_scc1 .LBB0_856
	s_cmp_gt_i32 s19, 3
	s_cbranch_scc0 .LBB0_857
	v_pk_mul_f32 v[36:37], v[30:31], s[78:79] op_sel_hi:[1,0]
	v_pk_mul_f32 v[34:35], v[28:29], s[78:79] op_sel_hi:[1,0]
	v_pk_mul_f32 v[40:41], v[26:27], s[78:79] op_sel_hi:[1,0]
	v_pk_mul_f32 v[38:39], v[24:25], s[78:79] op_sel_hi:[1,0]
	s_mov_b64 s[10:11], -1
	s_cbranch_execz .LBB0_858
	s_branch .LBB0_859

.LBB0_885:
	s_nop 1
	v_fmamk_f32 v16, v151, 0x3a800000, v219
	s_cmp_lt_i32 s19, 3
	v_rsq_f32_e32 v17, v16
	v_add_u32_e32 v19, 0xb0, v150
	s_nop 0
	v_mov_b32_e32 v28, v17
	v_mov_b64_e32 v[16:17], s[42:43]
	v_mad_i64_i32 v[24:25], s[8:9], v19, s70, v[16:17]
	v_pk_mul_f32 v[14:15], v[14:15], v[28:29] op_sel_hi:[1,0]
	v_pk_mul_f32 v[12:13], v[12:13], v[28:29] op_sel_hi:[1,0]
	v_pk_mul_f32 v[10:11], v[10:11], v[28:29] op_sel_hi:[1,0]
	v_pk_mul_f32 v[8:9], v[8:9], v[28:29] op_sel_hi:[1,0]
	s_cbranch_scc1 .LBB0_888
	s_cmp_gt_i32 s19, 3
	s_cbranch_scc0 .LBB0_889
	v_pk_mul_f32 v[18:19], v[14:15], s[78:79] op_sel_hi:[1,0]
	v_pk_mul_f32 v[16:17], v[12:13], s[78:79] op_sel_hi:[1,0]
	v_pk_mul_f32 v[22:23], v[10:11], s[78:79] op_sel_hi:[1,0]
	v_pk_mul_f32 v[20:21], v[8:9], s[78:79] op_sel_hi:[1,0]
	s_mov_b64 s[10:11], -1
	s_cbranch_execz .LBB0_890
	s_branch .LBB0_891
